# attention QK^T: all four K-fragment LDS reads of a key tile issued up front into separate VGPR quads (one exposed LDS round trip per tile instead of three)
# baseline (speedup 1.0000x reference)
.Lat_norm:
	v_lshlrev_b32_e32 v66, 4, v164
	v_bitop3_b32 v66, v66, v107, s5 bitop3:0xde
	v_mad_u64_u32 v[74:75], s[44:45], v66, s35, v[110:111]
	ds_read_b128 v[66:69], v74
	ds_read_b128 v[70:73], v74 offset:64
	ds_read_b128 v[228:231], v74 offset:128
	ds_read_b128 v[232:235], v74 offset:192
	v_min_i32_e32 v165, 14, v163
	v_add_u32_e32 v166, 2, v163
	s_waitcnt lgkmcnt(3)
	v_mfma_f32_16x16x32_bf16 v[66:69], v[66:69], v[62:65], 0
	v_min_i32_e32 v167, 15, v166
	v_add_u32_e32 v168, 4, v163
	v_min_i32_e32 v169, 15, v168
	s_waitcnt lgkmcnt(2)
	v_mfma_f32_16x16x32_bf16 v[66:69], v[70:73], v[58:61], v[66:69]
	v_add_u32_e32 v170, 6, v163
	v_min_i32_e32 v171, 15, v170
	s_waitcnt lgkmcnt(1)
	v_mfma_f32_16x16x32_bf16 v[66:69], v[228:231], v[54:57], v[66:69]
	v_add_u32_e32 v182, 9, v163
	s_cmp_gt_i32 s14, 0
	s_waitcnt lgkmcnt(0)
	v_mfma_f32_16x16x32_bf16 v[66:69], v[232:235], v[50:53], v[66:69]
	v_lshl_add_u32 v70, v165, 4, 16
	v_bitop3_b32 v70, v70, v107, s5 bitop3:0xde
	v_mad_u64_u32 v[78:79], s[44:45], v70, s35, v[110:111]
	ds_read_b128 v[70:73], v78
	ds_read_b128 v[74:77], v78 offset:64
	ds_read_b128 v[236:239], v78 offset:128
	ds_read_b128 v[240:243], v78 offset:192
	s_waitcnt lgkmcnt(3)
	v_mfma_f32_16x16x32_bf16 v[70:73], v[70:73], v[62:65], 0
	v_cmp_lt_i32_e64 s[14:15], 7, v163
	v_cmp_gt_i32_e32 vcc, 16, v163
	v_or_b32_e32 v174, v175, v107
	s_waitcnt lgkmcnt(2)
	v_mfma_f32_16x16x32_bf16 v[70:73], v[74:77], v[58:61], v[70:73]
	v_ashrrev_i32_e32 v139, 31, v138
	s_waitcnt lgkmcnt(1)
	v_mfma_f32_16x16x32_bf16 v[70:73], v[236:239], v[54:57], v[70:73]
	s_waitcnt lgkmcnt(0)
	v_mfma_f32_16x16x32_bf16 v[70:73], v[240:243], v[50:53], v[70:73]
	v_lshlrev_b32_e32 v74, 4, v167
	v_bitop3_b32 v74, v74, v107, s5 bitop3:0xde
	v_mad_u64_u32 v[82:83], s[44:45], v74, s35, v[110:111]
	ds_read_b128 v[74:77], v82
	ds_read_b128 v[78:81], v82 offset:64
	ds_read_b128 v[228:231], v82 offset:128
	ds_read_b128 v[232:235], v82 offset:192
	s_waitcnt lgkmcnt(3)
	v_mfma_f32_16x16x32_bf16 v[74:77], v[74:77], v[62:65], 0
	s_waitcnt lgkmcnt(2)
	v_mfma_f32_16x16x32_bf16 v[74:77], v[78:81], v[58:61], v[74:77]
	s_waitcnt lgkmcnt(1)
	v_mfma_f32_16x16x32_bf16 v[74:77], v[228:231], v[54:57], v[74:77]
	s_waitcnt lgkmcnt(0)
	v_mfma_f32_16x16x32_bf16 v[74:77], v[232:235], v[50:53], v[74:77]
	v_min_i32_e32 v78, 12, v163
	v_lshl_add_u32 v78, v78, 4, 48
	v_bitop3_b32 v78, v78, v107, s5 bitop3:0xde
	v_mad_u64_u32 v[86:87], s[44:45], v78, s35, v[110:111]
	ds_read_b128 v[78:81], v86
	ds_read_b128 v[82:85], v86 offset:64
	ds_read_b128 v[236:239], v86 offset:128
	ds_read_b128 v[240:243], v86 offset:192
	s_waitcnt lgkmcnt(3)
	v_mfma_f32_16x16x32_bf16 v[78:81], v[78:81], v[62:65], 0
	s_waitcnt lgkmcnt(2)
	v_mfma_f32_16x16x32_bf16 v[78:81], v[82:85], v[58:61], v[78:81]
	s_waitcnt lgkmcnt(1)
	v_mfma_f32_16x16x32_bf16 v[78:81], v[236:239], v[54:57], v[78:81]
	s_waitcnt lgkmcnt(0)
	v_mfma_f32_16x16x32_bf16 v[78:81], v[240:243], v[50:53], v[78:81]
	v_lshlrev_b32_e32 v82, 4, v169
	v_bitop3_b32 v82, v82, v107, s5 bitop3:0xde
	v_mad_u64_u32 v[90:91], s[44:45], v82, s35, v[110:111]
	ds_read_b128 v[82:85], v90
	ds_read_b128 v[86:89], v90 offset:64
	ds_read_b128 v[228:231], v90 offset:128
	ds_read_b128 v[232:235], v90 offset:192
	s_waitcnt lgkmcnt(3)
	v_mfma_f32_16x16x32_bf16 v[82:85], v[82:85], v[62:65], 0
	s_waitcnt lgkmcnt(2)
	v_mfma_f32_16x16x32_bf16 v[82:85], v[86:89], v[58:61], v[82:85]
	s_waitcnt lgkmcnt(1)
	v_mfma_f32_16x16x32_bf16 v[82:85], v[228:231], v[54:57], v[82:85]
	s_waitcnt lgkmcnt(0)
	v_mfma_f32_16x16x32_bf16 v[82:85], v[232:235], v[50:53], v[82:85]
	v_min_i32_e32 v86, 10, v163
	v_lshl_add_u32 v86, v86, 4, v201
	v_bitop3_b32 v86, v86, v107, s5 bitop3:0xde
	v_mad_u64_u32 v[94:95], s[44:45], v86, s35, v[110:111]
	ds_read_b128 v[86:89], v94
	ds_read_b128 v[90:93], v94 offset:64
	ds_read_b128 v[236:239], v94 offset:128
	ds_read_b128 v[240:243], v94 offset:192
	s_waitcnt lgkmcnt(3)
	v_mfma_f32_16x16x32_bf16 v[86:89], v[86:89], v[62:65], 0
	s_waitcnt lgkmcnt(2)
	v_mfma_f32_16x16x32_bf16 v[86:89], v[90:93], v[58:61], v[86:89]
	s_waitcnt lgkmcnt(1)
	v_mfma_f32_16x16x32_bf16 v[86:89], v[236:239], v[54:57], v[86:89]
	s_waitcnt lgkmcnt(0)
	v_mfma_f32_16x16x32_bf16 v[86:89], v[240:243], v[50:53], v[86:89]
	v_lshlrev_b32_e32 v90, 4, v171
	v_bitop3_b32 v90, v90, v107, s5 bitop3:0xde
	v_mad_u64_u32 v[98:99], s[44:45], v90, s35, v[110:111]
	ds_read_b128 v[90:93], v98
	ds_read_b128 v[94:97], v98 offset:64
	ds_read_b128 v[228:231], v98 offset:128
	ds_read_b128 v[232:235], v98 offset:192
	s_waitcnt lgkmcnt(3)
	v_mfma_f32_16x16x32_bf16 v[90:93], v[90:93], v[62:65], 0
	s_waitcnt lgkmcnt(2)
	v_mfma_f32_16x16x32_bf16 v[90:93], v[94:97], v[58:61], v[90:93]
	s_waitcnt lgkmcnt(1)
	v_mfma_f32_16x16x32_bf16 v[90:93], v[228:231], v[54:57], v[90:93]
	s_waitcnt lgkmcnt(0)
	v_mfma_f32_16x16x32_bf16 v[90:93], v[232:235], v[50:53], v[90:93]
	v_min_i32_e32 v94, 8, v163
	v_lshl_add_u32 v94, v94, 4, v202
	v_bitop3_b32 v94, v94, v107, s5 bitop3:0xde
	v_mad_u64_u32 v[172:173], s[44:45], v94, s35, v[110:111]
	ds_read_b128 v[94:97], v172
	ds_read_b128 v[98:101], v172 offset:64
	ds_read_b128 v[236:239], v172 offset:128
	ds_read_b128 v[240:243], v172 offset:192
	s_waitcnt lgkmcnt(3)
	v_mfma_f32_16x16x32_bf16 v[94:97], v[94:97], v[62:65], 0
	s_waitcnt lgkmcnt(2)
	v_mfma_f32_16x16x32_bf16 v[94:97], v[98:101], v[58:61], v[94:97]
	s_waitcnt lgkmcnt(1)
	v_mfma_f32_16x16x32_bf16 v[94:97], v[236:239], v[54:57], v[94:97]
	v_add_u32_e32 v172, 8, v163
	v_min_i32_e32 v173, 15, v172
	s_waitcnt lgkmcnt(0)
	v_mfma_f32_16x16x32_bf16 v[98:101], v[240:243], v[50:53], v[94:97]
	s_nop 2
	v_lshlrev_b32_e32 v94, 4, v173
	v_bitop3_b32 v94, v94, v107, s5 bitop3:0xde
	v_mad_u64_u32 v[180:181], s[44:45], v94, s35, v[110:111]
	ds_read_b128 v[94:97], v180
	ds_read_b128 v[176:179], v180 offset:64
	ds_read_b128 v[228:231], v180 offset:128
	ds_read_b128 v[232:235], v180 offset:192
	s_waitcnt lgkmcnt(3)
	v_mfma_f32_16x16x32_bf16 v[94:97], v[94:97], v[62:65], 0
	s_waitcnt lgkmcnt(2)
	v_mfma_f32_16x16x32_bf16 v[94:97], v[176:179], v[58:61], v[94:97]
	s_waitcnt lgkmcnt(1)
	v_mfma_f32_16x16x32_bf16 v[94:97], v[228:231], v[54:57], v[94:97]
	s_waitcnt lgkmcnt(0)
	v_mfma_f32_16x16x32_bf16 v[94:97], v[232:235], v[50:53], v[94:97]
	v_min_i32_e32 v176, 15, v182
	v_lshlrev_b32_e32 v176, 4, v176
	v_bitop3_b32 v176, v176, v107, s5 bitop3:0xde
	v_mad_u64_u32 v[180:181], s[44:45], v176, s35, v[110:111]
	ds_read_b128 v[176:179], v180
	ds_read_b128 v[236:239], v180 offset:64
	ds_read_b128 v[240:243], v180 offset:128
	ds_read_b128 v[244:247], v180 offset:192
	s_waitcnt lgkmcnt(3)
	v_mfma_f32_16x16x32_bf16 v[62:65], v[176:179], v[62:65], 0
	s_cselect_b64 s[44:45], -1, 0
	s_or_b64 s[14:15], s[44:45], s[14:15]
	s_waitcnt lgkmcnt(2)
	v_mfma_f32_16x16x32_bf16 v[58:61], v[236:239], v[58:61], v[62:65]
	s_nop 2
	s_and_b64 s[14:15], vcc, s[14:15]
	s_xor_b64 s[50:51], s[14:15], -1
	s_waitcnt lgkmcnt(1)
	v_mfma_f32_16x16x32_bf16 v[54:57], v[240:243], v[54:57], v[58:61]
	s_nop 2
	s_or_b64 s[52:53], s[50:51], s[12:13]
	v_mul_f32_e32 v62, 0x3e0293ee, v72
	s_waitcnt lgkmcnt(0)
	v_mfma_f32_16x16x32_bf16 v[50:53], v[244:247], v[50:53], v[54:57]
	s_nop 2
	v_add_u32_e32 v54, 0x80, v174
	v_or_b32_e32 v55, v175, v145
	v_cmp_gt_i32_e32 vcc, v55, v54
	s_or_b64 vcc, s[52:53], vcc
	v_mul_f32_e32 v56, 0x3e0293ee, v66
	v_or_b32_e32 v57, 1, v55
	v_cndmask_b32_e32 v56, v56, v203, vcc
	v_cmp_ge_i32_e32 vcc, v57, v174
	s_and_b64 s[14:15], s[14:15], vcc
	v_cmp_lt_i32_e32 vcc, v55, v54
	s_and_b64 vcc, s[14:15], vcc
	v_mul_f32_e32 v57, 0x3e0293ee, v67
	v_or_b32_e32 v59, 2, v55
	v_cndmask_b32_e32 v57, v203, v57, vcc
	v_cmp_lt_i32_e32 vcc, v59, v174
	s_or_b64 s[14:15], s[50:51], vcc
	v_cmp_gt_i32_e32 vcc, v59, v54
	s_or_b64 vcc, s[14:15], vcc
	v_mul_f32_e32 v59, 0x3e0293ee, v68
	v_or_b32_e32 v55, 3, v55
	v_cndmask_b32_e32 v59, v59, v203, vcc
	v_cmp_lt_i32_e32 vcc, v55, v174
	s_or_b64 s[14:15], s[50:51], vcc
	v_cmp_gt_i32_e32 vcc, v55, v54
	s_or_b64 vcc, s[14:15], vcc
	v_mul_f32_e32 v55, 0x3e0293ee, v69
	v_cmp_lt_i32_e64 s[14:15], 6, v163
	v_cndmask_b32_e32 v55, v55, v203, vcc
	v_cmp_gt_i32_e32 vcc, 15, v163
	s_or_b64 s[14:15], s[44:45], s[14:15]
	s_and_b64 vcc, vcc, s[14:15]
	v_mul_f32_e32 v60, 0x3e0293ee, v70
	v_mul_f32_e32 v61, 0x3e0293ee, v71
	v_mul_f32_e32 v63, 0x3e0293ee, v73
	v_cmp_lt_i32_e64 s[14:15], 5, v163
	v_cndmask_b32_e32 v60, v203, v60, vcc
	v_cndmask_b32_e32 v61, v203, v61, vcc
	v_cndmask_b32_e32 v62, v203, v62, vcc
	v_cndmask_b32_e32 v63, v203, v63, vcc
	v_cmp_gt_i32_e32 vcc, 14, v163
	s_or_b64 s[14:15], s[44:45], s[14:15]
	s_and_b64 vcc, vcc, s[14:15]
	v_mul_f32_e32 v64, 0x3e0293ee, v74
	v_mul_f32_e32 v65, 0x3e0293ee, v75
	v_mul_f32_e32 v66, 0x3e0293ee, v76
	v_mul_f32_e32 v67, 0x3e0293ee, v77
	v_cmp_lt_i32_e64 s[14:15], 4, v163
	v_cndmask_b32_e32 v64, v203, v64, vcc
	v_cndmask_b32_e32 v65, v203, v65, vcc
	v_cndmask_b32_e32 v66, v203, v66, vcc
	v_cndmask_b32_e32 v67, v203, v67, vcc
	v_cmp_gt_i32_e32 vcc, 13, v163
	s_or_b64 s[14:15], s[44:45], s[14:15]
	s_and_b64 vcc, vcc, s[14:15]
	v_mul_f32_e32 v68, 0x3e0293ee, v78
	v_mul_f32_e32 v69, 0x3e0293ee, v79
	v_mul_f32_e32 v70, 0x3e0293ee, v80
	v_mul_f32_e32 v71, 0x3e0293ee, v81
	v_cmp_lt_i32_e64 s[14:15], 3, v163
	v_cndmask_b32_e32 v68, v203, v68, vcc
	v_cndmask_b32_e32 v69, v203, v69, vcc
	v_cndmask_b32_e32 v70, v203, v70, vcc
	v_cndmask_b32_e32 v71, v203, v71, vcc
	v_cmp_gt_i32_e32 vcc, 12, v163
	s_or_b64 s[14:15], s[44:45], s[14:15]
	s_and_b64 vcc, vcc, s[14:15]
	v_mul_f32_e32 v72, 0x3e0293ee, v82
	v_mul_f32_e32 v73, 0x3e0293ee, v83
	v_mul_f32_e32 v74, 0x3e0293ee, v84
	v_mul_f32_e32 v75, 0x3e0293ee, v85
	v_cmp_lt_i32_e64 s[14:15], 2, v163
	v_cndmask_b32_e32 v72, v203, v72, vcc
	v_cndmask_b32_e32 v73, v203, v73, vcc
	v_cndmask_b32_e32 v74, v203, v74, vcc
	v_cndmask_b32_e32 v75, v203, v75, vcc
	v_cmp_gt_i32_e32 vcc, 11, v163
	s_or_b64 s[14:15], s[44:45], s[14:15]
	s_and_b64 vcc, vcc, s[14:15]
	v_mul_f32_e32 v77, 0x3e0293ee, v87
	v_cndmask_b32_e32 v84, v203, v77, vcc
	v_mul_f32_e32 v77, 0x3e0293ee, v88
	v_mul_f32_e32 v76, 0x3e0293ee, v86
	v_cndmask_b32_e32 v85, v203, v77, vcc
	v_mul_f32_e32 v77, 0x3e0293ee, v89
	v_cmp_lt_i32_e64 s[14:15], 1, v163
	v_cndmask_b32_e32 v76, v203, v76, vcc
	v_cndmask_b32_e32 v86, v203, v77, vcc
	v_cmp_gt_i32_e32 vcc, 10, v163
	s_or_b64 s[14:15], s[44:45], s[14:15]
	s_and_b64 vcc, vcc, s[14:15]
	v_mul_f32_e32 v77, 0x3e0293ee, v90
	v_cndmask_b32_e32 v87, v203, v77, vcc
	v_mul_f32_e32 v77, 0x3e0293ee, v91
	v_cndmask_b32_e32 v88, v203, v77, vcc
	v_mul_f32_e32 v77, 0x3e0293ee, v92
	v_cndmask_b32_e32 v89, v203, v77, vcc
	v_mul_f32_e32 v77, 0x3e0293ee, v93
	v_cmp_lt_i32_e64 s[14:15], 0, v163
	v_cndmask_b32_e32 v90, v203, v77, vcc
	v_cmp_gt_i32_e32 vcc, 9, v163
	s_or_b64 s[14:15], s[44:45], s[14:15]
	s_and_b64 vcc, vcc, s[14:15]
	v_mul_f32_e32 v77, 0x3e0293ee, v98
	v_cndmask_b32_e32 v91, v203, v77, vcc
	v_mul_f32_e32 v77, 0x3e0293ee, v99
	v_cndmask_b32_e32 v92, v203, v77, vcc
	v_mul_f32_e32 v77, 0x3e0293ee, v100
	v_cndmask_b32_e32 v93, v203, v77, vcc
	v_mul_f32_e32 v77, 0x3e0293ee, v101
	v_cmp_lt_i32_e64 s[14:15], -1, v163
	v_cndmask_b32_e32 v98, v203, v77, vcc
	v_cmp_gt_i32_e32 vcc, 8, v163
	s_or_b64 s[14:15], s[44:45], s[14:15]
	s_and_b64 s[14:15], vcc, s[14:15]
	v_lshl_or_b32 v77, v172, 4, v145
	v_cmp_lt_i32_e32 vcc, v77, v174
	s_xor_b64 s[50:51], s[14:15], -1
	s_or_b64 s[52:53], s[50:51], vcc
	v_cmp_gt_i32_e32 vcc, v77, v54
	s_or_b64 vcc, s[52:53], vcc
	v_mul_f32_e32 v78, 0x3e0293ee, v94
	v_cndmask_b32_e32 v99, v78, v203, vcc
	v_or_b32_e32 v78, 1, v77
	v_cmp_ge_i32_e32 vcc, v78, v174
	s_and_b64 s[14:15], s[14:15], vcc
	v_cmp_lt_i32_e32 vcc, v77, v54
	s_and_b64 vcc, s[14:15], vcc
	v_mul_f32_e32 v78, 0x3e0293ee, v95
	v_cndmask_b32_e32 v100, v203, v78, vcc
	v_or_b32_e32 v78, 2, v77
	v_cmp_lt_i32_e32 vcc, v78, v174
	s_or_b64 s[14:15], s[50:51], vcc
	v_cmp_gt_i32_e32 vcc, v78, v54
	s_or_b64 vcc, s[14:15], vcc
	v_mul_f32_e32 v78, 0x3e0293ee, v96
	v_or_b32_e32 v77, 3, v77
	v_cndmask_b32_e32 v101, v78, v203, vcc
	v_cmp_lt_i32_e32 vcc, v77, v174
	s_or_b64 s[14:15], s[50:51], vcc
	v_cmp_gt_i32_e32 vcc, v77, v54
	s_mov_b32 s5, 0xff61b1e6
	s_or_b64 vcc, s[14:15], vcc
	v_mul_f32_e32 v77, 0x3e0293ee, v97
	v_cmp_lt_i32_e64 s[14:15], -2, v163
	v_max3_f32 v58, v56, s5, v57
	v_cndmask_b32_e32 v175, v77, v203, vcc
	v_cmp_gt_i32_e32 vcc, 7, v163
	s_or_b64 s[14:15], s[44:45], s[14:15]
	v_max3_f32 v58, v58, v59, v55
	s_and_b64 s[14:15], vcc, s[14:15]
	v_lshl_or_b32 v77, v182, 4, v145
	v_max3_f32 v58, v58, v60, v61
	v_cmp_lt_i32_e32 vcc, v77, v174
	s_xor_b64 s[44:45], s[14:15], -1
	v_max3_f32 v58, v58, v62, v63
	s_or_b64 s[50:51], s[44:45], vcc
	v_cmp_gt_i32_e32 vcc, v77, v54
	v_max3_f32 v58, v58, v64, v65
	s_or_b64 vcc, s[50:51], vcc
	v_mul_f32_e32 v50, 0x3e0293ee, v50
	v_max3_f32 v58, v58, v66, v67
	v_cndmask_b32_e32 v176, v50, v203, vcc
	v_or_b32_e32 v50, 1, v77
	v_max3_f32 v58, v58, v68, v69
	v_cmp_ge_i32_e32 vcc, v50, v174
	v_max3_f32 v58, v58, v70, v71
	s_and_b64 s[14:15], s[14:15], vcc
	v_cmp_lt_i32_e32 vcc, v77, v54
	v_max3_f32 v58, v58, v72, v73
	s_and_b64 vcc, s[14:15], vcc
	v_mul_f32_e32 v50, 0x3e0293ee, v51
	v_or_b32_e32 v51, 2, v77
	v_max3_f32 v58, v58, v74, v75
	v_cndmask_b32_e32 v177, v203, v50, vcc
	v_cmp_lt_i32_e32 vcc, v51, v174
	v_max3_f32 v58, v58, v76, v84
	s_or_b64 s[14:15], s[44:45], vcc
	v_cmp_gt_i32_e32 vcc, v51, v54
	v_max3_f32 v58, v58, v85, v86
	s_or_b64 vcc, s[14:15], vcc
	v_mul_f32_e32 v51, 0x3e0293ee, v52
	v_max3_f32 v58, v58, v87, v88
	v_cndmask_b32_e32 v178, v51, v203, vcc
	v_or_b32_e32 v51, 3, v77
	v_max3_f32 v58, v58, v89, v90
	v_cmp_lt_i32_e32 vcc, v51, v174
	v_max3_f32 v58, v58, v91, v92
	s_or_b64 s[14:15], s[44:45], vcc
	v_cmp_gt_i32_e32 vcc, v51, v54
	v_max3_f32 v58, v58, v93, v98
	s_or_b64 vcc, s[14:15], vcc
	v_mul_f32_e32 v51, 0x3e0293ee, v53
	v_and_b32_e32 v52, 64, v197
	v_max3_f32 v58, v58, v99, v100
	v_cndmask_b32_e32 v174, v51, v203, vcc
	v_xor_b32_e32 v51, 16, v197
	v_add_u32_e32 v52, 64, v52
	v_max3_f32 v58, v58, v101, v175
	v_cmp_lt_i32_e32 vcc, v51, v52
	v_max3_f32 v50, v58, v176, v177
	v_max3_f32 v50, v50, v178, v174
	v_cndmask_b32_e32 v51, v197, v51, vcc
	v_lshlrev_b32_e32 v179, 2, v51
	ds_bpermute_b32 v51, v179, v50
	s_waitcnt lgkmcnt(0)
	v_max_f32_e32 v51, v51, v51
	v_max_f32_e32 v50, v50, v51
	v_xor_b32_e32 v51, 32, v197
	v_cmp_lt_i32_e32 vcc, v51, v52
	s_nop 1
	v_cndmask_b32_e32 v51, v197, v51, vcc
	v_lshlrev_b32_e32 v180, 2, v51
	ds_bpermute_b32 v51, v180, v50
	s_waitcnt lgkmcnt(0)
	v_max_f32_e32 v51, v51, v51
	v_max_f32_e32 v181, v50, v51
	v_sub_f32_e32 v50, v56, v181
	v_exp_f32_e32 v50, v50
	v_sub_f32_e32 v51, v57, v181
	v_exp_f32_e32 v51, v51
	v_add_f32_e32 v52, 0, v50
	v_add_f32_e32 v53, v51, v52
	v_sub_f32_e32 v52, v59, v181
	v_exp_f32_e32 v52, v52
	s_nop 0
	v_add_f32_e32 v54, v52, v53
	v_sub_f32_e32 v53, v55, v181
	v_exp_f32_e32 v53, v53
	s_nop 0
	v_add_f32_e32 v55, v53, v54
	v_sub_f32_e32 v54, v60, v181
	v_exp_f32_e32 v54, v54
	s_nop 0
	v_add_f32_e32 v56, v54, v55
	v_sub_f32_e32 v55, v61, v181
	v_exp_f32_e32 v55, v55
	s_nop 0
	v_add_f32_e32 v57, v55, v56
	v_sub_f32_e32 v56, v62, v181
	v_exp_f32_e32 v56, v56
	s_nop 0
	v_add_f32_e32 v58, v56, v57
	v_sub_f32_e32 v57, v63, v181
	v_exp_f32_e32 v57, v57
	v_sub_f32_e32 v63, v68, v181
	v_add_f32_e32 v59, v57, v58
	v_sub_f32_e32 v58, v64, v181
	v_exp_f32_e32 v58, v58
	v_exp_f32_e32 v64, v63
	v_sub_f32_e32 v63, v69, v181
	v_add_f32_e32 v60, v58, v59
	v_sub_f32_e32 v59, v65, v181
	v_exp_f32_e32 v59, v59
	v_exp_f32_e32 v65, v63
	v_sub_f32_e32 v63, v70, v181
	v_exp_f32_e32 v77, v63
	v_add_f32_e32 v61, v59, v60
	v_sub_f32_e32 v60, v66, v181
	v_exp_f32_e32 v60, v60
	v_sub_f32_e32 v63, v71, v181
	v_exp_f32_e32 v78, v63
	v_sub_f32_e32 v63, v72, v181
	v_add_f32_e32 v62, v60, v61
	v_sub_f32_e32 v61, v67, v181
	v_exp_f32_e32 v61, v61
	v_exp_f32_e32 v79, v63
	v_sub_f32_e32 v63, v73, v181
	v_exp_f32_e32 v80, v63
	v_add_f32_e32 v62, v61, v62
	v_add_f32_e32 v62, v64, v62
	v_add_f32_e32 v62, v65, v62
	v_sub_f32_e32 v63, v74, v181
	v_add_f32_e32 v62, v77, v62
	v_exp_f32_e32 v81, v63
	v_sub_f32_e32 v63, v75, v181
	v_add_f32_e32 v62, v78, v62
	v_exp_f32_e32 v82, v63
	v_sub_f32_e32 v63, v76, v181
	v_add_f32_e32 v62, v79, v62
	v_exp_f32_e32 v83, v63
	v_sub_f32_e32 v63, v84, v181
	v_add_f32_e32 v62, v80, v62
	v_exp_f32_e32 v84, v63
	v_sub_f32_e32 v63, v85, v181
	v_add_f32_e32 v62, v81, v62
	v_exp_f32_e32 v85, v63
	v_sub_f32_e32 v63, v86, v181
	v_add_f32_e32 v62, v82, v62
	v_exp_f32_e32 v86, v63
	v_sub_f32_e32 v63, v87, v181
	v_add_f32_e32 v62, v83, v62
	v_exp_f32_e32 v87, v63
	v_sub_f32_e32 v63, v88, v181
	v_add_f32_e32 v62, v84, v62
	v_exp_f32_e32 v88, v63
	v_sub_f32_e32 v63, v89, v181
	v_add_f32_e32 v62, v85, v62
	v_exp_f32_e32 v89, v63
	v_sub_f32_e32 v63, v90, v181
	v_add_f32_e32 v62, v86, v62
	v_exp_f32_e32 v90, v63
	v_sub_f32_e32 v63, v91, v181
	v_add_f32_e32 v62, v87, v62
	v_exp_f32_e32 v91, v63
	v_sub_f32_e32 v63, v92, v181
	v_add_f32_e32 v62, v88, v62
	v_exp_f32_e32 v92, v63
	v_sub_f32_e32 v63, v93, v181
	v_add_f32_e32 v62, v89, v62
	v_exp_f32_e32 v93, v63
	v_sub_f32_e32 v63, v98, v181
	v_add_f32_e32 v62, v90, v62
	v_exp_f32_e32 v94, v63
	v_sub_f32_e32 v63, v99, v181
	v_add_f32_e32 v62, v91, v62
	v_exp_f32_e32 v95, v63
	v_sub_f32_e32 v63, v100, v181
	v_add_f32_e32 v62, v92, v62
	v_exp_f32_e32 v96, v63
	v_sub_f32_e32 v63, v101, v181
	v_add_f32_e32 v62, v93, v62
	v_exp_f32_e32 v97, v63
	v_sub_f32_e32 v63, v175, v181
	v_add_f32_e32 v62, v94, v62
	v_exp_f32_e32 v98, v63
	v_sub_f32_e32 v63, v176, v181
	v_add_f32_e32 v62, v95, v62
	v_exp_f32_e32 v99, v63
	v_sub_f32_e32 v63, v177, v181
	v_add_f32_e32 v62, v96, v62
	v_exp_f32_e32 v100, v63
	v_sub_f32_e32 v63, v178, v181
	v_add_f32_e32 v62, v97, v62
	v_exp_f32_e32 v101, v63
	v_sub_f32_e32 v63, v174, v181
	v_add_f32_e32 v62, v98, v62
	v_exp_f32_e32 v174, v63
	v_add_f32_e32 v62, v99, v62
	v_add_f32_e32 v62, v100, v62
	v_add_f32_e32 v62, v101, v62
	v_add_f32_e32 v62, v174, v62
	ds_bpermute_b32 v63, v179, v62
	v_mov_b32_e32 v76, 0
	s_waitcnt lgkmcnt(0)
	v_add_f32_e32 v66, v62, v63
	ds_bpermute_b32 v67, v180, v66
	v_lshl_add_u64 v[62:63], s[96:97], 0, v[138:139]
	s_waitcnt lgkmcnt(0)
	v_add_f32_e32 v68, v66, v67
	v_div_scale_f32 v66, s[14:15], v68, v68, 1.0
	v_rcp_f32_e32 v67, v66
	s_nop 0
	v_fma_f32 v69, -v66, v67, 1.0
	v_fmac_f32_e32 v67, v69, v67
	v_div_scale_f32 v69, vcc, 1.0, v68, 1.0
	v_mul_f32_e32 v70, v69, v67
	v_fma_f32 v71, -v66, v70, v69
	v_fmac_f32_e32 v70, v71, v67
	v_fma_f32 v66, -v66, v70, v69
	v_div_fmas_f32 v66, v66, v67, v70
	v_div_fixup_f32 v72, v66, v68, 1.0
	v_lshlrev_b64 v[66:67], 12, v[62:63]
	v_lshl_add_u64 v[70:71], v[136:137], 0, v[66:67]
	v_log_f32_e32 v66, v68
	v_lshlrev_b64 v[62:63], 6, v[62:63]
	s_andn2_b64 vcc, exec, s[94:95]
	v_lshl_add_u64 v[74:75], s[64:65], 0, v[62:63]
	v_add_f32_e32 v66, v181, v66
	v_mul_f32_e32 v73, 0x3f317218, v66
	s_cbranch_vccnz .LBB0_1108
	v_max_f32_e32 v66, v73, v73
	s_mov_b32 s5, 0x800000
	s_waitcnt vmcnt(0)
	v_max_f32_e32 v63, v226, v226
	v_max_f32_e32 v63, v63, v66
	v_sub_f32_e32 v62, v226, v63
	v_sub_f32_e32 v66, v73, v63
	v_mul_f32_e32 v62, 0x3fb8aa3b, v62
	v_mul_f32_e32 v66, 0x3fb8aa3b, v66
	v_exp_f32_e32 v62, v62
	v_exp_f32_e32 v66, v66
	s_nop 0
	v_add_f32_e32 v67, v62, v66
	v_div_scale_f32 v68, s[14:15], v67, v67, 1.0
	v_rcp_f32_e32 v69, v68
	s_nop 0
	v_fma_f32 v73, -v68, v69, 1.0
	v_fmac_f32_e32 v69, v73, v69
	v_div_scale_f32 v73, vcc, 1.0, v67, 1.0
	v_mul_f32_e32 v76, v73, v69
	v_fma_f32 v138, -v68, v76, v73
	v_fmac_f32_e32 v76, v138, v69
	v_fma_f32 v68, -v68, v76, v73
	v_div_fmas_f32 v68, v68, v69, v76
	v_div_fixup_f32 v68, v68, v67, 1.0
	v_mul_f32_e32 v76, v62, v68
	v_mul_f32_e32 v62, v66, v68
	v_cmp_gt_f32_e32 vcc, s5, v67
	v_mul_f32_e32 v72, v72, v62
	s_mov_b32 s5, 0x3f317217
	v_cndmask_b32_e64 v62, 0, 32, vcc
	v_ldexp_f32 v62, v67, v62
	v_log_f32_e32 v62, v62
	s_nop 0
	v_mul_f32_e32 v66, 0x3f317217, v62
	v_fma_f32 v66, v62, s5, -v66
	v_fmac_f32_e32 v66, 0x3377d1cf, v62
	s_mov_b32 s5, 0x7f800000
	v_fmac_f32_e32 v66, 0x3f317217, v62
	v_cmp_lt_f32_e64 s[14:15], |v62|, s5
	s_nop 1
	v_cndmask_b32_e64 v62, v62, v66, s[14:15]
	v_cndmask_b32_e32 v66, 0, v204, vcc
	v_sub_f32_e32 v62, v62, v66
	v_add_f32_e32 v73, v63, v62
